# v75 + a safety s_nop 7 between the last PV MFMA (reads v[64:67] as SrcC) and the VALU write of v64
# speedup vs baseline: 1.0038x; 1.0038x over previous
; #define LAS __attribute__((address_space(3)))
; __device__ __forceinline__ void attn_phase(const Params& p, LAS unsigned char* lds, int tid, int G, int bid) {
;     ...
;         float mx = -INFINITY;
; #pragma unroll
;         for (int tt = 0; tt < 10; ++tt)
; #pragma unroll
;             for (int j = 0; j < 4; ++j) { const int kj = 16 * (tstart + tt) + 4 * quad + j, delta = qi + 128 - kj;
;                 const bool valid = (delta >= 0) && (delta <= 128) && (nb > 0 || kj >= 128);
;                 const float v = valid ? s[tt][j] - sl2 * (float)delta : -INFINITY; s[tt][j] = v; mx = fmaxf(mx, v); }
;         mx = fmaxf(mx, __shfl_xor(mx, 16)); mx = fmaxf(mx, __shfl_xor(mx, 32));
;         float den = 0.f;
; #pragma unroll
;         for (int tt = 0; tt < 10; ++tt)
; #pragma unroll
;             for (int j = 0; j < 4; ++j) { const float e = __builtin_amdgcn_exp2f(s[tt][j] - mx); s[tt][j] = e; den += e; }
;         den += __shfl_xor(den, 16); den += __shfl_xor(den, 32);
;         f32x4 o[4];
; #pragma unroll
;         for (int dt = 0; dt < 4; ++dt) o[dt] = (f32x4){0.f, 0.f, 0.f, 0.f};
; #pragma unroll
;         for (int c = 0; c < 5; ++c) {
;             int p0_ = 0, p1_ = 0;
;             p0_ = __builtin_amdgcn_cvt_pk_fp8_f32(s[2 * c][0], s[2 * c][1], p0_, false); p0_ = __builtin_amdgcn_cvt_pk_fp8_f32(s[2 * c][2], s[2 * c][3], p0_, true);
;             p1_ = __builtin_amdgcn_cvt_pk_fp8_f32(s[2 * c + 1][0], s[2 * c + 1][1], p1_, false); p1_ = __builtin_amdgcn_cvt_pk_fp8_f32(s[2 * c + 1][2], s[2 * c + 1][3], p1_, true);
;             const long pf = (long)(((unsigned long long)(unsigned)p1_ << 32) | (unsigned long long)(unsigned)p0_);
; #pragma unroll
;             for (int dt = 0; dt < 4; ++dt) { const LAS unsigned char* vp = lds + VT_OFF + (16 * dt + fr) * VT_PITCH + 16 * (tstart + 2 * c) + 4 * quad;
;                 const unsigned lo = *(const LAS unsigned*)vp, hi = *(const LAS unsigned*)(vp + 16);
;                 const long vf = (long)(((unsigned long long)hi << 32) | (unsigned long long)lo);
;                 o[dt] = __builtin_amdgcn_mfma_f32_16x16x32_fp8_fp8(vf, pf, o[dt], 0, 0, 0); }
.Lattn_nb_ok:
	s_mov_b32 s12, 0xff800000
	v_max3_f32 v118, v62, s12, v63
	v_max3_f32 v118, v118, v116, v117
	v_max3_f32 v118, v118, v114, v115
	v_max3_f32 v118, v118, v112, v113
	v_max3_f32 v118, v118, v110, v111
	v_max3_f32 v118, v118, v108, v109
	v_max3_f32 v118, v118, v106, v107
	v_max3_f32 v118, v118, v104, v105
	v_max3_f32 v118, v118, v82, v83
	v_max3_f32 v118, v118, v80, v81
	v_max3_f32 v118, v118, v78, v79
	v_max3_f32 v118, v118, v76, v77
	v_max3_f32 v118, v118, v74, v75
	v_max3_f32 v118, v118, v72, v73
	v_max3_f32 v118, v118, v70, v71
	v_max3_f32 v118, v118, v68, v69
	v_max3_f32 v118, v118, v66, v67
	v_max3_f32 v118, v118, v64, v65
	v_max3_f32 v118, v118, v60, v61
	v_max3_f32 v9, v118, v10, v11
	v_mov_b32_e32 v118, v9
	v_mov_b32_e32 v213, v9
	s_nop 1
	v_permlane16_swap_b32_e32 v118, v213
	v_max_f32_e32 v9, v118, v213
	v_mov_b32_e32 v118, v9
	v_mov_b32_e32 v213, v9
	s_nop 1
	v_permlane32_swap_b32_e32 v118, v213
	v_max_f32_e32 v9, v118, v213
	v_sub_f32_e32 v62, v62, v9
	v_exp_f32_e32 v62, v62
	v_sub_f32_e32 v63, v63, v9
	v_exp_f32_e32 v63, v63
	v_sub_f32_e32 v116, v116, v9
	v_exp_f32_e32 v116, v116
	v_sub_f32_e32 v117, v117, v9
	v_exp_f32_e32 v117, v117
	v_sub_f32_e32 v114, v114, v9
	v_add_f32_e32 v118, 0, v62
	v_exp_f32_e32 v114, v114
	v_sub_f32_e32 v115, v115, v9
	v_add_f32_e32 v118, v63, v118
	v_exp_f32_e32 v115, v115
	v_sub_f32_e32 v112, v112, v9
	v_add_f32_e32 v118, v116, v118
	v_exp_f32_e32 v112, v112
	v_sub_f32_e32 v113, v113, v9
	v_add_f32_e32 v118, v117, v118
	v_exp_f32_e32 v113, v113
	v_sub_f32_e32 v110, v110, v9
	v_add_f32_e32 v118, v114, v118
	v_exp_f32_e32 v110, v110
	v_sub_f32_e32 v111, v111, v9
	v_add_f32_e32 v118, v115, v118
	v_exp_f32_e32 v111, v111
	v_sub_f32_e32 v108, v108, v9
	v_add_f32_e32 v118, v112, v118
	v_exp_f32_e32 v108, v108
	v_sub_f32_e32 v109, v109, v9
	v_add_f32_e32 v118, v113, v118
	v_exp_f32_e32 v109, v109
	v_sub_f32_e32 v106, v106, v9
	v_add_f32_e32 v118, v110, v118
	v_exp_f32_e32 v106, v106
	v_sub_f32_e32 v107, v107, v9
	v_add_f32_e32 v118, v111, v118
	v_exp_f32_e32 v107, v107
	v_sub_f32_e32 v104, v104, v9
	v_add_f32_e32 v118, v108, v118
	v_exp_f32_e32 v104, v104
	v_sub_f32_e32 v105, v105, v9
	v_add_f32_e32 v118, v109, v118
	v_exp_f32_e32 v105, v105
	v_sub_f32_e32 v82, v82, v9
	v_add_f32_e32 v118, v106, v118
	v_exp_f32_e32 v82, v82
	v_sub_f32_e32 v83, v83, v9
	v_add_f32_e32 v118, v107, v118
	v_exp_f32_e32 v83, v83
	v_sub_f32_e32 v80, v80, v9
	v_add_f32_e32 v118, v104, v118
	v_exp_f32_e32 v80, v80
	v_sub_f32_e32 v81, v81, v9
	v_add_f32_e32 v118, v105, v118
	v_exp_f32_e32 v81, v81
	v_sub_f32_e32 v78, v78, v9
	v_add_f32_e32 v118, v82, v118
	v_exp_f32_e32 v78, v78
	v_sub_f32_e32 v79, v79, v9
	v_add_f32_e32 v118, v83, v118
	v_exp_f32_e32 v79, v79
	v_sub_f32_e32 v76, v76, v9
	v_add_f32_e32 v118, v80, v118
	v_exp_f32_e32 v119, v76
	v_add_f32_e32 v118, v81, v118
	v_add_f32_e32 v118, v78, v118
	v_add_f32_e32 v118, v79, v118
	v_sub_f32_e32 v77, v77, v9
	v_add_f32_e32 v76, v119, v118
	v_exp_f32_e32 v118, v77
	v_sub_f32_e32 v74, v74, v9
	v_exp_f32_e32 v186, v74
	v_sub_f32_e32 v75, v75, v9
	v_exp_f32_e32 v187, v75
	v_sub_f32_e32 v72, v72, v9
	v_exp_f32_e32 v188, v72
	v_sub_f32_e32 v73, v73, v9
	v_add_f32_e32 v76, v118, v76
	v_exp_f32_e32 v189, v73
	v_sub_f32_e32 v70, v70, v9
	v_add_f32_e32 v74, v186, v76
	v_exp_f32_e32 v190, v70
	v_sub_f32_e32 v71, v71, v9
	v_add_f32_e32 v74, v187, v74
	v_exp_f32_e32 v191, v71
	v_sub_f32_e32 v68, v68, v9
	v_add_f32_e32 v72, v188, v74
	v_exp_f32_e32 v192, v68
	v_sub_f32_e32 v69, v69, v9
	v_add_f32_e32 v72, v189, v72
	v_exp_f32_e32 v193, v69
	v_sub_f32_e32 v66, v66, v9
	v_add_f32_e32 v70, v190, v72
	v_exp_f32_e32 v194, v66
	v_sub_f32_e32 v67, v67, v9
	v_add_f32_e32 v70, v191, v70
	v_exp_f32_e32 v195, v67
	v_sub_f32_e32 v64, v64, v9
	v_add_f32_e32 v68, v192, v70
	v_exp_f32_e32 v196, v64
	v_sub_f32_e32 v65, v65, v9
	v_add_f32_e32 v68, v193, v68
	v_exp_f32_e32 v197, v65
	v_sub_f32_e32 v60, v60, v9
	v_add_f32_e32 v66, v194, v68
	v_exp_f32_e32 v198, v60
	v_sub_f32_e32 v61, v61, v9
	v_add_f32_e32 v66, v195, v66
	v_exp_f32_e32 v199, v61
	v_sub_f32_e32 v10, v10, v9
	v_add_f32_e32 v64, v196, v66
	v_exp_f32_e32 v200, v10
	v_sub_f32_e32 v11, v11, v9
	v_add_f32_e32 v64, v197, v64
	v_exp_f32_e32 v201, v11
	v_add_f32_e32 v60, v198, v64
	v_add_f32_e32 v60, v199, v60
	v_add_f32_e32 v10, v200, v60
	v_add_f32_e32 v10, v201, v10
	v_mov_b32_e32 v11, v10
	v_mov_b32_e32 v213, v10
	s_nop 1
	v_permlane16_swap_b32_e32 v11, v213
	v_add_f32_e32 v202, v11, v213
	v_cvt_pk_fp8_f32 v11, v114, v115
	v_cvt_pk_fp8_f32 v11, v112, v113 op_sel:[0,0,1]
	ds_read_b64_tr_b8 v[60:61], v246 offset:0
	ds_read_b64_tr_b8 v[64:65], v246 offset:16
	ds_read_b64_tr_b8 v[68:69], v246 offset:32
	ds_read_b64_tr_b8 v[72:73], v246 offset:48
	ds_read_b64_tr_b8 v[214:215], v246 offset:2560
	ds_read_b64_tr_b8 v[216:217], v246 offset:2576
	ds_read_b64_tr_b8 v[218:219], v246 offset:2592
	ds_read_b64_tr_b8 v[220:221], v246 offset:2608
	ds_read_b64_tr_b8 v[222:223], v246 offset:5120
	ds_read_b64_tr_b8 v[224:225], v246 offset:5136
	ds_read_b64_tr_b8 v[226:227], v246 offset:5152
	ds_read_b64_tr_b8 v[228:229], v246 offset:5168
	v_cvt_pk_fp8_f32 v10, v62, v63
	v_mov_b32_e32 v203, v202
	v_mov_b32_e32 v213, v202
	s_nop 1
	v_permlane32_swap_b32_e32 v203, v213
	v_add_f32_e32 v203, v203, v213
	v_cvt_pk_fp8_f32 v10, v116, v117 op_sel:[0,0,1]
	s_waitcnt lgkmcnt(8)
; #define LAS __attribute__((address_space(3)))
; __device__ __forceinline__ float f8c(float v) { return fminf(fmaxf(v, -448.f), 448.f); }
; #define LDS_WAIT() asm volatile("s_waitcnt lgkmcnt(0)" ::: "memory")
; __device__ __forceinline__ void attn_phase(const Params& p, LAS unsigned char* lds, int tid, int G, int bid) {
;     ...
;         for (int c = 0; c < 5; ++c) {
;             int p0_ = 0, p1_ = 0;
;             p0_ = __builtin_amdgcn_cvt_pk_fp8_f32(s[2 * c][0], s[2 * c][1], p0_, false); p0_ = __builtin_amdgcn_cvt_pk_fp8_f32(s[2 * c][2], s[2 * c][3], p0_, true);
;             p1_ = __builtin_amdgcn_cvt_pk_fp8_f32(s[2 * c + 1][0], s[2 * c + 1][1], p1_, false); p1_ = __builtin_amdgcn_cvt_pk_fp8_f32(s[2 * c + 1][2], s[2 * c + 1][3], p1_, true);
;             const long pf = (long)(((unsigned long long)(unsigned)p1_ << 32) | (unsigned long long)(unsigned)p0_);
; #pragma unroll
;             for (int dt = 0; dt < 4; ++dt) { const LAS unsigned char* vp = lds + VT_OFF + (16 * dt + fr) * VT_PITCH + 16 * (tstart + 2 * c) + 4 * quad;
;                 const unsigned lo = *(const LAS unsigned*)vp, hi = *(const LAS unsigned*)(vp + 16);
;                 const long vf = (long)(((unsigned long long)hi << 32) | (unsigned long long)lo);
;                 o[dt] = __builtin_amdgcn_mfma_f32_16x16x32_fp8_fp8(vf, pf, o[dt], 0, 0, 0); }
;         }
;         const float inv = 1.0f / den;
;         { LAS unsigned char* ost = lds + OST_OFF + w * 2304;
; #pragma unroll
;           for (int dt = 0; dt < 4; ++dt) { int wv = 0; wv = __builtin_amdgcn_cvt_pk_fp8_f32(f8c(o[dt][0] * inv), f8c(o[dt][1] * inv), wv, false); wv = __builtin_amdgcn_cvt_pk_fp8_f32(f8c(o[dt][2] * inv), f8c(o[dt][3] * inv), wv, true);
;               *(LAS unsigned*)(ost + fr * 80 + 16 * dt + 4 * quad) = (unsigned)wv; }
;           LDS_WAIT();
;           const int q2 = lane >> 2, ck = lane & 3, tq2 = ((nb * 128 + 16 * w + q2) << dsh) + r;
;           const u32x4 r0 = *(const LAS u32x4*)(ost + q2 * 80 + ck * 16);
;           unsigned char* op = (unsigned char*)OG + ((size_t)g * M + (size_t)b * SEQ + tq2) * AOW + hh * 64 + ck * 16;
;           *(u32x4*)op = r0; }
;         if (quad == 0) LSE[(size_t)uid * 128 + qi] = (mx + __builtin_amdgcn_logf(den)) * LN2F;
	s_nop 0
	v_mfma_f32_16x16x32_fp8_fp8 v[60:63], v[60:61], v[10:11], 0
	v_mfma_f32_16x16x32_fp8_fp8 v[64:67], v[64:65], v[10:11], 0
	v_mfma_f32_16x16x32_fp8_fp8 v[68:71], v[68:69], v[10:11], 0
	v_mfma_f32_16x16x32_fp8_fp8 v[72:75], v[72:73], v[10:11], 0
	ds_read_b64_tr_b8 v[230:231], v246 offset:7680
	ds_read_b64_tr_b8 v[232:233], v246 offset:7696
	ds_read_b64_tr_b8 v[234:235], v246 offset:7712
	ds_read_b64_tr_b8 v[236:237], v246 offset:7728
	v_cvt_pk_fp8_f32 v10, v110, v111
	v_cvt_pk_fp8_f32 v11, v106, v107
	v_cvt_pk_fp8_f32 v10, v108, v109 op_sel:[0,0,1]
	v_cvt_pk_fp8_f32 v11, v104, v105 op_sel:[0,0,1]
	s_waitcnt lgkmcnt(8)
	s_nop 0
	v_mfma_f32_16x16x32_fp8_fp8 v[60:63], v[214:215], v[10:11], v[60:63]
	v_mfma_f32_16x16x32_fp8_fp8 v[64:67], v[216:217], v[10:11], v[64:67]
	v_mfma_f32_16x16x32_fp8_fp8 v[68:71], v[218:219], v[10:11], v[68:71]
	v_mfma_f32_16x16x32_fp8_fp8 v[72:75], v[220:221], v[10:11], v[72:75]
	ds_read_b64_tr_b8 v[238:239], v246 offset:10240
	ds_read_b64_tr_b8 v[240:241], v246 offset:10256
	ds_read_b64_tr_b8 v[242:243], v246 offset:10272
	ds_read_b64_tr_b8 v[244:245], v246 offset:10288
	v_cvt_pk_fp8_f32 v10, v82, v83
	v_cvt_pk_fp8_f32 v11, v78, v79
	v_cvt_pk_fp8_f32 v10, v80, v81 op_sel:[0,0,1]
	v_cvt_pk_fp8_f32 v11, v119, v118 op_sel:[0,0,1]
	s_waitcnt lgkmcnt(8)
	s_nop 0
	v_mfma_f32_16x16x32_fp8_fp8 v[60:63], v[222:223], v[10:11], v[60:63]
	v_mfma_f32_16x16x32_fp8_fp8 v[64:67], v[224:225], v[10:11], v[64:67]
	v_mfma_f32_16x16x32_fp8_fp8 v[68:71], v[226:227], v[10:11], v[68:71]
	v_mfma_f32_16x16x32_fp8_fp8 v[72:75], v[228:229], v[10:11], v[72:75]
	v_cvt_pk_fp8_f32 v10, v186, v187
	v_cvt_pk_fp8_f32 v11, v190, v191
	v_cvt_pk_fp8_f32 v10, v188, v189 op_sel:[0,0,1]
	v_cvt_pk_fp8_f32 v11, v192, v193 op_sel:[0,0,1]
	s_waitcnt lgkmcnt(4)
	s_nop 0
	v_mfma_f32_16x16x32_fp8_fp8 v[60:63], v[230:231], v[10:11], v[60:63]
	v_mfma_f32_16x16x32_fp8_fp8 v[64:67], v[232:233], v[10:11], v[64:67]
	v_mfma_f32_16x16x32_fp8_fp8 v[68:71], v[234:235], v[10:11], v[68:71]
	v_mfma_f32_16x16x32_fp8_fp8 v[72:75], v[236:237], v[10:11], v[72:75]
	v_cvt_pk_fp8_f32 v10, v194, v195
	v_cvt_pk_fp8_f32 v11, v198, v199
	v_cvt_pk_fp8_f32 v10, v196, v197 op_sel:[0,0,1]
	v_cvt_pk_fp8_f32 v11, v200, v201 op_sel:[0,0,1]
	s_waitcnt lgkmcnt(0)
	s_nop 0
	v_mfma_f32_16x16x32_fp8_fp8 v[60:63], v[238:239], v[10:11], v[60:63]
	v_mfma_f32_16x16x32_fp8_fp8 v[76:79], v[240:241], v[10:11], v[64:67]
	v_mfma_f32_16x16x32_fp8_fp8 v[214:217], v[242:243], v[10:11], v[68:71]
	v_mfma_f32_16x16x32_fp8_fp8 v[218:221], v[244:245], v[10:11], v[72:75]
	s_nop 7
	v_mov_b32_e32 v64, v203
	v_div_scale_f32 v10, s[6:7], v64, v64, 1.0
	v_rcp_f32_e32 v11, v10
	s_nop 0
	v_fma_f32 v65, -v10, v11, 1.0
	v_fmac_f32_e32 v11, v65, v11
	v_div_scale_f32 v65, vcc, 1.0, v64, 1.0
	v_mul_f32_e32 v74, v65, v11
	v_fma_f32 v75, -v10, v74, v65
	v_fmac_f32_e32 v74, v75, v11
	v_fma_f32 v10, -v10, v74, v65
	v_div_fmas_f32 v10, v10, v11, v74
	v_div_fixup_f32 v10, v10, v64, 1.0
	v_mul_f32_e32 v11, v10, v60
	v_mul_f32_e32 v60, v10, v61
	v_med3_f32 v11, v11, s81, v185
	v_med3_f32 v60, v60, s81, v185
	v_cvt_pk_fp8_f32 v61, v11, v60
	v_mul_f32_e32 v11, v10, v62
	v_mul_f32_e32 v60, v10, v63
	v_med3_f32 v11, v11, s81, v185
	v_med3_f32 v60, v60, s81, v185
	v_cvt_pk_fp8_f32 v61, v11, v60 op_sel:[0,0,1]
	v_mul_f32_e32 v11, v10, v76
	v_mul_f32_e32 v60, v10, v77
	v_med3_f32 v11, v11, s81, v185
	v_med3_f32 v60, v60, s81, v185
	v_cvt_pk_fp8_f32 v62, v11, v60
	v_mul_f32_e32 v11, v10, v78
	v_mul_f32_e32 v60, v10, v79
	v_med3_f32 v11, v11, s81, v185
	v_med3_f32 v60, v60, s81, v185
	v_cvt_pk_fp8_f32 v62, v11, v60 op_sel:[0,0,1]
	v_mul_f32_e32 v11, v10, v214
	v_mul_f32_e32 v60, v10, v215
	v_med3_f32 v11, v11, s81, v185
	ds_write2_b32 v181, v61, v62 offset1:4
	v_med3_f32 v60, v60, s81, v185
	v_cvt_pk_fp8_f32 v61, v11, v60
	v_mul_f32_e32 v11, v10, v216
	v_mul_f32_e32 v60, v10, v217
	v_med3_f32 v11, v11, s81, v185
	v_med3_f32 v60, v60, s81, v185
	v_cvt_pk_fp8_f32 v61, v11, v60 op_sel:[0,0,1]
	v_mul_f32_e32 v11, v10, v218
	v_mul_f32_e32 v60, v10, v219
	v_med3_f32 v11, v11, s81, v185
	v_med3_f32 v60, v60, s81, v185
	v_cvt_pk_fp8_f32 v62, v11, v60
	v_mul_f32_e32 v11, v10, v220
	v_mul_f32_e32 v10, v10, v221
	v_med3_f32 v11, v11, s81, v185
	v_med3_f32 v10, v10, s81, v185
	v_cvt_pk_fp8_f32 v62, v11, v10 op_sel:[0,0,1]
	v_lshl_add_u32 v10, s86, 7, v124
	v_lshlrev_b32_e32 v10, s1, v10
	v_add_u32_e32 v10, s5, v10
	s_ashr_i32 s5, s4, 31
	s_ashr_i32 s1, s0, 31
	s_lshl_b64 s[4:5], s[4:5], 15
	s_lshl_b64 s[0:1], s[0:1], 11
	ds_write2_b32 v181, v61, v62 offset0:8 offset1:12
	s_add_u32 s0, s4, s0
	s_waitcnt lgkmcnt(0)
	s_addc_u32 s1, s5, s1
	v_ashrrev_i32_e32 v11, 31, v10
	ds_read_b128 v[60:63], v182
	v_lshl_add_u64 v[10:11], s[0:1], 0, v[10:11]
	v_lshlrev_b64 v[10:11], 8, v[10:11]
	v_lshl_add_u64 v[10:11], s[94:95], 0, v[10:11]
	s_lshl_b32 s86, s11, 6
	v_lshl_add_u64 v[10:11], v[10:11], 0, s[86:87]
	v_lshl_add_u64 v[10:11], v[10:11], 0, v[84:85]
	s_waitcnt lgkmcnt(0)
	global_store_dwordx4 v[10:11], v[60:63], off
	s_mov_b64 s[0:1], exec
	v_readlane_b32 s4, v250, 35
	v_readlane_b32 s5, v250, 36
	s_and_b64 s[4:5], s[0:1], s[4:5]
	s_mov_b64 exec, s[4:5]
	s_cbranch_execz .LBB0_286
	v_log_f32_e32 v10, v64
	s_nop 0
	v_add_f32_e32 v9, v9, v10
	v_mul_f32_e32 v9, 0x3f317218, v9
	global_store_dword v[98:99], v9, off
